# attention: stride-advanced staging addresses + wave-0-only tail, row-max self-max canonicalisations dropped, shift ballot read from the compare mask directly (s_and vcc) instead of cndmask+cmp, +0 add
# speedup vs baseline: 1.0272x; 1.0070x over previous
.LBB0_846:
	s_andn2_saveexec_b64 s[68:69], s[68:69]
	v_lshlrev_b64 v[64:65], 10, v[66:67]
	v_lshl_add_u64 v[64:65], v[156:157], 0, v[64:65]
	s_or_b64 exec, exec, s[68:69]
	v_mov_b32_e32 v152, v64
	v_mov_b32_e32 v153, v65
	s_andn2_b64 vcc, s[12:13], s[14:15]
	v_mov_b32_e32 v154, 0x10000
	v_mov_b32_e32 v67, 0x1000
	v_cndmask_b32_e32 v154, v154, v67, vcc
	v_mov_b32_e32 v155, 0
	v_readfirstlane_b32 s98, v191
	v_add_u32_e32 v66, s35, v191
	s_nop 0
	v_readfirstlane_b32 s30, v66
	s_mov_b32 m0, s30
	s_nop 0
	global_load_lds_dwordx4 v[64:65], off
	s_or_b64 exec, exec, s[66:67]
	s_and_saveexec_b64 s[66:67], s[6:7]
	s_cbranch_execz .LBB0_838

.LBB0_855:
	s_andn2_saveexec_b64 s[68:69], s[68:69]
	v_lshlrev_b64 v[64:65], 10, v[66:67]
	v_lshl_add_u64 v[64:65], v[162:163], 0, v[64:65]
	s_or_b64 exec, exec, s[68:69]
	v_mov_b32_e32 v158, v64
	v_mov_b32_e32 v159, v65
	s_andn2_b64 vcc, s[16:17], s[18:19]
	v_mov_b32_e32 v160, 0x10000
	v_mov_b32_e32 v67, 0x1000
	v_cndmask_b32_e32 v160, v160, v67, vcc
	v_mov_b32_e32 v161, 0
	v_readfirstlane_b32 s99, v196
	v_add_u32_e32 v66, s35, v196
	s_nop 0
	v_readfirstlane_b32 s30, v66
	s_mov_b32 m0, s30
	s_nop 0
	global_load_lds_dwordx4 v[64:65], off
	s_or_b64 exec, exec, s[66:67]
	s_and_saveexec_b64 s[66:67], s[8:9]
	s_cbranch_execz .LBB0_839

.LBB0_864:
	s_andn2_saveexec_b64 s[68:69], s[68:69]
	v_lshlrev_b64 v[64:65], 10, v[66:67]
	v_lshl_add_u64 v[64:65], v[168:169], 0, v[64:65]
	s_or_b64 exec, exec, s[68:69]
	v_mov_b32_e32 v164, v64
	v_mov_b32_e32 v165, v65
	s_andn2_b64 vcc, s[20:21], s[22:23]
	v_mov_b32_e32 v166, 0x10000
	v_mov_b32_e32 v67, 0x1000
	v_cndmask_b32_e32 v166, v166, v67, vcc
	v_mov_b32_e32 v167, 0
	v_readfirstlane_b32 s100, v189
	v_add_u32_e32 v66, s35, v189
	s_nop 0
	v_readfirstlane_b32 s30, v66
	s_mov_b32 m0, s30
	s_nop 0
	global_load_lds_dwordx4 v[64:65], off
	s_or_b64 exec, exec, s[66:67]
	s_and_saveexec_b64 s[66:67], s[10:11]
	s_cbranch_execz .LBB0_876

.LBB0_873:
	s_andn2_saveexec_b64 s[28:29], s[28:29]
	v_lshlrev_b64 v[64:65], 10, v[66:67]
	v_lshl_add_u64 v[64:65], v[174:175], 0, v[64:65]
	s_or_b64 exec, exec, s[28:29]
	v_mov_b32_e32 v170, v64
	v_mov_b32_e32 v171, v65
	s_andn2_b64 vcc, s[24:25], s[26:27]
	v_mov_b32_e32 v172, 0x10000
	v_mov_b32_e32 v67, 0x1000
	v_cndmask_b32_e32 v172, v172, v67, vcc
	v_mov_b32_e32 v173, 0
	v_readfirstlane_b32 s101, v197
	v_add_u32_e32 v66, s35, v197
	s_nop 0
	v_readfirstlane_b32 s28, v66
	s_mov_b32 m0, s28
	s_nop 0
	global_load_lds_dwordx4 v[64:65], off

.Lhwat0_fast:
	s_mov_b64 s[68:69], 0x80
	s_add_u32 m0, s98, s35
	v_lshl_add_u64 v[152:153], v[152:153], 0, v[154:155]
	global_load_lds_dwordx4 v[152:153], off
	s_add_u32 m0, s99, s35
	v_lshl_add_u64 v[158:159], v[158:159], 0, v[160:161]
	global_load_lds_dwordx4 v[158:159], off
	s_add_u32 m0, s100, s35
	v_lshl_add_u64 v[164:165], v[164:165], 0, v[166:167]
	global_load_lds_dwordx4 v[164:165], off
	s_add_u32 s30, s98, s35
	s_add_u32 m0, s30, 0x3400
	v_lshl_add_u64 v[176:177], v[176:177], 0, s[68:69]
	global_load_lds_dwordx4 v[176:177], off
	s_add_u32 s30, s99, s35
	s_add_u32 m0, s30, 0x3400
	v_lshl_add_u64 v[180:181], v[180:181], 0, s[68:69]
	global_load_lds_dwordx4 v[180:181], off
	s_and_saveexec_b64 s[66:67], s[10:11]
	s_cbranch_execz .Lhwat0_tail
	s_add_u32 m0, s101, s35
	v_lshl_add_u64 v[170:171], v[170:171], 0, v[172:173]
	global_load_lds_dwordx4 v[170:171], off
	s_add_u32 s30, s100, s35
	s_add_u32 m0, s30, 0x3400
	v_lshl_add_u64 v[148:149], v[148:149], 0, s[68:69]
	global_load_lds_dwordx4 v[148:149], off

.LBB0_885:
	s_nop 10
	v_max_f32_e32 v203, v80, v81
	v_max3_f32 v203, v203, v82, v83
	v_max3_f32 v203, v203, v84, v85
	v_max3_f32 v203, v203, v86, v87
	v_max3_f32 v203, v203, v88, v89
	v_max3_f32 v203, v203, v90, v91
	v_max3_f32 v203, v203, v92, v93
	v_max3_f32 v203, v203, v94, v95
	v_mov_b32_e32 v204, v203
	s_nop 1
	v_permlane32_swap_b32_e32 v203, v204
	v_max_f32_e32 v204, v203, v204
	v_max_f32_e32 v203, v64, v65
	v_max3_f32 v203, v203, v66, v67
	v_max3_f32 v203, v203, v68, v69
	v_max3_f32 v203, v203, v70, v71
	v_max3_f32 v203, v203, v72, v73
	v_max3_f32 v203, v203, v74, v75
	v_max3_f32 v203, v203, v76, v77
	v_max3_f32 v203, v203, v78, v79
	v_mov_b32_e32 v205, v203
	s_nop 1
	v_permlane32_swap_b32_e32 v203, v205
	v_max_f32_e32 v203, v203, v205
	v_max_f32_e32 v205, v204, v203
	v_cmp_lt_f32_e32 vcc, s83, v205
	v_min_f32_e32 v205, v204, v203
	v_cmp_gt_f32_e64 s[28:29], s84, v205
	s_and_b64 s[28:29], s[64:65], s[28:29]
	s_or_b64 s[28:29], vcc, s[28:29]
	s_and_b64 vcc, exec, s[28:29]
	s_cbranch_vccz .LBB0_887
	v_max_f32_e32 v205, v204, v204
	v_max_f32_e32 v205, 0, v205
	v_cndmask_b32_e64 v204, v205, v204, s[64:65]
	v_exp_f32_e64 v206, -v204
	v_add_f32_e32 v199, v199, v204
	v_pk_add_f32 v[80:81], v[80:81], v[204:205] op_sel_hi:[1,0] neg_lo:[0,1] neg_hi:[0,1]
	v_pk_add_f32 v[82:83], v[82:83], v[204:205] op_sel_hi:[1,0] neg_lo:[0,1] neg_hi:[0,1]
	v_pk_add_f32 v[84:85], v[84:85], v[204:205] op_sel_hi:[1,0] neg_lo:[0,1] neg_hi:[0,1]
	v_pk_add_f32 v[86:87], v[86:87], v[204:205] op_sel_hi:[1,0] neg_lo:[0,1] neg_hi:[0,1]
	v_pk_add_f32 v[88:89], v[88:89], v[204:205] op_sel_hi:[1,0] neg_lo:[0,1] neg_hi:[0,1]
	v_pk_add_f32 v[90:91], v[90:91], v[204:205] op_sel_hi:[1,0] neg_lo:[0,1] neg_hi:[0,1]
	v_pk_add_f32 v[92:93], v[92:93], v[204:205] op_sel_hi:[1,0] neg_lo:[0,1] neg_hi:[0,1]
	v_pk_add_f32 v[94:95], v[94:95], v[204:205] op_sel_hi:[1,0] neg_lo:[0,1] neg_hi:[0,1]
	v_max_f32_e32 v204, v203, v203
	v_max_f32_e32 v204, 0, v204
	v_cndmask_b32_e64 v204, v204, v203, s[64:65]
	v_exp_f32_e64 v208, -v204
	v_mov_b32_e32 v209, v206
	v_pk_mul_f32 v[62:63], v[62:63], v[206:207] op_sel_hi:[1,0]
	v_pk_mul_f32 v[60:61], v[60:61], v[206:207] op_sel_hi:[1,0]
	v_pk_mul_f32 v[58:59], v[58:59], v[206:207] op_sel_hi:[1,0]
	v_pk_mul_f32 v[56:57], v[56:57], v[206:207] op_sel_hi:[1,0]
	v_pk_mul_f32 v[54:55], v[54:55], v[206:207] op_sel_hi:[1,0]
	v_pk_mul_f32 v[52:53], v[52:53], v[206:207] op_sel_hi:[1,0]
	v_pk_mul_f32 v[50:51], v[50:51], v[206:207] op_sel_hi:[1,0]
	v_pk_mul_f32 v[48:49], v[48:49], v[206:207] op_sel_hi:[1,0]
	v_pk_mul_f32 v[46:47], v[46:47], v[206:207] op_sel_hi:[1,0]
	v_pk_mul_f32 v[44:45], v[44:45], v[206:207] op_sel_hi:[1,0]
	v_pk_mul_f32 v[42:43], v[42:43], v[206:207] op_sel_hi:[1,0]
	v_pk_mul_f32 v[40:41], v[40:41], v[206:207] op_sel_hi:[1,0]
	v_pk_mul_f32 v[38:39], v[38:39], v[206:207] op_sel_hi:[1,0]
	v_pk_mul_f32 v[36:37], v[36:37], v[206:207] op_sel_hi:[1,0]
	v_pk_mul_f32 v[34:35], v[34:35], v[206:207] op_sel_hi:[1,0]
	v_pk_mul_f32 v[32:33], v[32:33], v[206:207] op_sel_hi:[1,0]
	v_add_f32_e32 v200, v200, v204
	v_pk_mul_f32 v[150:151], v[150:151], v[208:209]
	v_pk_add_f32 v[64:65], v[64:65], v[204:205] op_sel_hi:[1,0] neg_lo:[0,1] neg_hi:[0,1]
	v_pk_add_f32 v[66:67], v[66:67], v[204:205] op_sel_hi:[1,0] neg_lo:[0,1] neg_hi:[0,1]
	v_pk_add_f32 v[68:69], v[68:69], v[204:205] op_sel_hi:[1,0] neg_lo:[0,1] neg_hi:[0,1]
	v_pk_add_f32 v[70:71], v[70:71], v[204:205] op_sel_hi:[1,0] neg_lo:[0,1] neg_hi:[0,1]
	v_pk_add_f32 v[72:73], v[72:73], v[204:205] op_sel_hi:[1,0] neg_lo:[0,1] neg_hi:[0,1]
	v_pk_add_f32 v[74:75], v[74:75], v[204:205] op_sel_hi:[1,0] neg_lo:[0,1] neg_hi:[0,1]
	v_pk_add_f32 v[76:77], v[76:77], v[204:205] op_sel_hi:[1,0] neg_lo:[0,1] neg_hi:[0,1]
	v_pk_add_f32 v[78:79], v[78:79], v[204:205] op_sel_hi:[1,0] neg_lo:[0,1] neg_hi:[0,1]
	v_pk_mul_f32 v[30:31], v[30:31], v[208:209] op_sel_hi:[1,0]
	v_pk_mul_f32 v[28:29], v[28:29], v[208:209] op_sel_hi:[1,0]
	v_pk_mul_f32 v[26:27], v[26:27], v[208:209] op_sel_hi:[1,0]
	v_pk_mul_f32 v[24:25], v[24:25], v[208:209] op_sel_hi:[1,0]
	v_pk_mul_f32 v[22:23], v[22:23], v[208:209] op_sel_hi:[1,0]
	v_pk_mul_f32 v[20:21], v[20:21], v[208:209] op_sel_hi:[1,0]
	v_pk_mul_f32 v[18:19], v[18:19], v[208:209] op_sel_hi:[1,0]
	v_pk_mul_f32 v[16:17], v[16:17], v[208:209] op_sel_hi:[1,0]
	v_pk_mul_f32 v[14:15], v[14:15], v[208:209] op_sel_hi:[1,0]
	v_pk_mul_f32 v[12:13], v[12:13], v[208:209] op_sel_hi:[1,0]
	v_pk_mul_f32 v[10:11], v[10:11], v[208:209] op_sel_hi:[1,0]
	v_pk_mul_f32 v[8:9], v[8:9], v[208:209] op_sel_hi:[1,0]
	v_pk_mul_f32 v[6:7], v[6:7], v[208:209] op_sel_hi:[1,0]
	v_pk_mul_f32 v[4:5], v[4:5], v[208:209] op_sel_hi:[1,0]
	v_pk_mul_f32 v[2:3], v[2:3], v[208:209] op_sel_hi:[1,0]
	v_pk_mul_f32 v[0:1], v[0:1], v[208:209] op_sel_hi:[1,0]
	s_mov_b64 s[62:63], -1
.LBB0_887:
	v_lshl_add_u32 v203, s68, 6, v202
	v_exp_f32_e32 v209, v80
	v_exp_f32_e32 v211, v81
	v_exp_f32_e32 v213, v82
	v_exp_f32_e32 v215, v83
	ds_read_b128 v[80:83], v203 offset:13312
	ds_read_b128 v[204:207], v203 offset:17920
	v_exp_f32_e32 v217, v84
	v_exp_f32_e32 v219, v85
	v_exp_f32_e32 v221, v86
	v_exp_f32_e32 v223, v87
	v_exp_f32_e32 v208, v64
	v_exp_f32_e32 v210, v65
	v_exp_f32_e32 v212, v66
	v_exp_f32_e32 v214, v67
	v_exp_f32_e32 v216, v68
	v_exp_f32_e32 v218, v69
	v_exp_f32_e32 v220, v70
	v_exp_f32_e32 v222, v71
	v_cvt_pk_bf16_f32 v64, v209, v211
	v_cvt_pk_bf16_f32 v65, v213, v215
	v_cvt_pk_bf16_f32 v66, v217, v219
	v_cvt_pk_bf16_f32 v67, v221, v223
	v_cvt_pk_bf16_f32 v68, v208, v210
	v_cvt_pk_bf16_f32 v69, v212, v214
	v_cvt_pk_bf16_f32 v70, v216, v218
	v_cvt_pk_bf16_f32 v71, v220, v222
	ds_read_b128 v[84:87], v203 offset:13344
	s_waitcnt lgkmcnt(0)
	v_mfma_f32_32x32x16_bf16 v[48:63], v[80:83], v[64:67], v[48:63]
	v_exp_f32_e32 v225, v88
	v_exp_f32_e32 v224, v72
	v_exp_f32_e32 v88, v73
	v_exp_f32_e32 v89, v89
	v_exp_f32_e32 v227, v90
	v_exp_f32_e32 v91, v91
	v_exp_f32_e32 v229, v92
	v_mfma_f32_32x32x16_bf16 v[16:31], v[80:83], v[68:71], v[16:31]
	ds_read_b128 v[80:83], v203 offset:17952
	v_exp_f32_e32 v93, v93
	v_exp_f32_e32 v231, v94
	v_exp_f32_e32 v95, v95
	v_exp_f32_e32 v226, v74
	v_exp_f32_e32 v90, v75
	v_exp_f32_e32 v228, v76
	v_mfma_f32_32x32x16_bf16 v[32:47], v[204:207], v[64:67], v[32:47]
	v_exp_f32_e32 v92, v77
	v_pk_add_f32 v[64:65], v[210:211], v[208:209]
	v_exp_f32_e32 v230, v78
	v_pk_add_f32 v[208:209], v[212:213], v[64:65]
	v_exp_f32_e32 v94, v79
	v_pk_add_f32 v[72:73], v[214:215], v[208:209]
	v_mfma_f32_32x32x16_bf16 v[0:15], v[204:207], v[68:71], v[0:15]
	v_add_f32_e64 v72, v216, v72
	v_add_f32_e64 v73, v217, v73
	v_cvt_pk_bf16_f32 v64, v225, v89
	v_add_f32_e64 v72, v218, v72
	v_add_f32_e64 v73, v219, v73
	v_cvt_pk_bf16_f32 v65, v227, v91
	v_pk_add_f32 v[72:73], v[220:221], v[72:73]
	v_cvt_pk_bf16_f32 v66, v229, v93
	v_pk_add_f32 v[72:73], v[222:223], v[72:73]
	v_cvt_pk_bf16_f32 v67, v231, v95
	v_cvt_pk_bf16_f32 v68, v224, v88
	v_cvt_pk_bf16_f32 v69, v226, v90
	v_cvt_pk_bf16_f32 v70, v228, v92
	v_cvt_pk_bf16_f32 v71, v230, v94
	v_pk_add_f32 v[72:73], v[224:225], v[72:73]
	v_mfma_f32_32x32x16_bf16 v[48:63], v[84:87], v[64:67], v[48:63]
	v_add_f32_e64 v72, v88, v72
	v_add_f32_e64 v73, v89, v73
	s_xor_b64 s[28:29], s[66:67], -1
	s_mov_b32 s68, 1
	s_mov_b64 s[66:67], 0
	s_and_b64 vcc, exec, s[28:29]
	v_mfma_f32_32x32x16_bf16 v[16:31], v[84:87], v[68:71], v[16:31]
	s_waitcnt lgkmcnt(0)
	v_mfma_f32_32x32x16_bf16 v[32:47], v[80:83], v[64:67], v[32:47]
	v_add_f32_e64 v64, v226, v72
	v_add_f32_e64 v65, v227, v73
	v_add_f32_e64 v64, v90, v64
	v_add_f32_e64 v65, v91, v65
	v_add_f32_e64 v64, v228, v64
	v_add_f32_e64 v65, v229, v65
	v_pk_add_f32 v[64:65], v[92:93], v[64:65]
	v_mfma_f32_32x32x16_bf16 v[0:15], v[80:83], v[68:71], v[0:15]
	v_add_f32_e64 v64, v230, v64
	v_add_f32_e64 v65, v231, v65
	v_add_f32_e64 v64, v94, v64
	v_add_f32_e64 v65, v95, v65
	v_add_f32_e64 v150, v150, v64
	v_add_f32_e64 v151, v151, v65
	s_cbranch_vccnz .LBB0_889
	s_mov_b64 s[64:65], 0
	s_and_b64 vcc, exec, s[62:63]
	v_lshl_or_b32 v203, s68, 5, v190
	s_mov_b64 s[28:29], -1
	s_cbranch_vccz .LBB0_882
	s_branch .LBB0_883

.LBB0_2080:
	s_andn2_saveexec_b64 s[68:69], s[68:69]
	v_lshlrev_b64 v[64:65], 10, v[66:67]
	v_lshl_add_u64 v[64:65], v[156:157], 0, v[64:65]
	s_or_b64 exec, exec, s[68:69]
	v_mov_b32_e32 v152, v64
	v_mov_b32_e32 v153, v65
	s_andn2_b64 vcc, s[14:15], s[16:17]
	v_mov_b32_e32 v154, 0x10000
	v_mov_b32_e32 v67, 0x1000
	v_cndmask_b32_e32 v154, v154, v67, vcc
	v_mov_b32_e32 v155, 0
	v_readfirstlane_b32 s98, v191
	v_add_u32_e32 v66, s89, v191
	s_nop 0
	v_readfirstlane_b32 s30, v66
	s_mov_b32 m0, s30
	s_nop 0
	global_load_lds_dwordx4 v[64:65], off
	s_or_b64 exec, exec, s[66:67]
	s_and_saveexec_b64 s[66:67], s[8:9]
	s_cbranch_execz .LBB0_2072

.LBB0_2089:
	s_andn2_saveexec_b64 s[68:69], s[68:69]
	v_lshlrev_b64 v[64:65], 10, v[66:67]
	v_lshl_add_u64 v[64:65], v[162:163], 0, v[64:65]
	s_or_b64 exec, exec, s[68:69]
	v_mov_b32_e32 v158, v64
	v_mov_b32_e32 v159, v65
	s_andn2_b64 vcc, s[18:19], s[20:21]
	v_mov_b32_e32 v160, 0x10000
	v_mov_b32_e32 v67, 0x1000
	v_cndmask_b32_e32 v160, v160, v67, vcc
	v_mov_b32_e32 v161, 0
	v_readfirstlane_b32 s99, v196
	v_add_u32_e32 v66, s89, v196
	s_nop 0
	v_readfirstlane_b32 s30, v66
	s_mov_b32 m0, s30
	s_nop 0
	global_load_lds_dwordx4 v[64:65], off
	s_or_b64 exec, exec, s[66:67]
	s_and_saveexec_b64 s[66:67], s[10:11]
	s_cbranch_execz .LBB0_2073

.LBB0_2098:
	s_andn2_saveexec_b64 s[68:69], s[68:69]
	v_lshlrev_b64 v[64:65], 10, v[66:67]
	v_lshl_add_u64 v[64:65], v[168:169], 0, v[64:65]
	s_or_b64 exec, exec, s[68:69]
	v_mov_b32_e32 v164, v64
	v_mov_b32_e32 v165, v65
	s_andn2_b64 vcc, s[22:23], s[24:25]
	v_mov_b32_e32 v166, 0x10000
	v_mov_b32_e32 v67, 0x1000
	v_cndmask_b32_e32 v166, v166, v67, vcc
	v_mov_b32_e32 v167, 0
	v_readfirstlane_b32 s100, v189
	v_add_u32_e32 v66, s89, v189
	s_nop 0
	v_readfirstlane_b32 s30, v66
	s_mov_b32 m0, s30
	s_nop 0
	global_load_lds_dwordx4 v[64:65], off
	s_or_b64 exec, exec, s[66:67]
	s_and_saveexec_b64 s[66:67], s[12:13]
	s_cbranch_execz .LBB0_2110

.LBB0_2107:
	s_andn2_saveexec_b64 s[34:35], s[34:35]
	v_lshlrev_b64 v[64:65], 10, v[66:67]
	v_lshl_add_u64 v[64:65], v[174:175], 0, v[64:65]
	s_or_b64 exec, exec, s[34:35]
	v_mov_b32_e32 v170, v64
	v_mov_b32_e32 v171, v65
	s_andn2_b64 vcc, s[26:27], s[28:29]
	v_mov_b32_e32 v172, 0x10000
	v_mov_b32_e32 v67, 0x1000
	v_cndmask_b32_e32 v172, v172, v67, vcc
	v_mov_b32_e32 v173, 0
	v_readfirstlane_b32 s101, v197
	v_add_u32_e32 v66, s89, v197
	s_nop 0
	v_readfirstlane_b32 s30, v66
	s_mov_b32 m0, s30
	s_nop 0
	global_load_lds_dwordx4 v[64:65], off

.Lhwat1_fast:
	s_mov_b64 s[68:69], 0x80
	s_add_u32 m0, s98, s89
	v_lshl_add_u64 v[152:153], v[152:153], 0, v[154:155]
	global_load_lds_dwordx4 v[152:153], off
	s_add_u32 m0, s99, s89
	v_lshl_add_u64 v[158:159], v[158:159], 0, v[160:161]
	global_load_lds_dwordx4 v[158:159], off
	s_add_u32 m0, s100, s89
	v_lshl_add_u64 v[164:165], v[164:165], 0, v[166:167]
	global_load_lds_dwordx4 v[164:165], off
	s_add_u32 s30, s98, s89
	s_add_u32 m0, s30, 0x3400
	v_lshl_add_u64 v[176:177], v[176:177], 0, s[68:69]
	global_load_lds_dwordx4 v[176:177], off
	s_add_u32 s30, s99, s89
	s_add_u32 m0, s30, 0x3400
	v_lshl_add_u64 v[180:181], v[180:181], 0, s[68:69]
	global_load_lds_dwordx4 v[180:181], off
	s_and_saveexec_b64 s[66:67], s[12:13]
	s_cbranch_execz .Lhwat1_tail
	s_add_u32 m0, s101, s89
	v_lshl_add_u64 v[170:171], v[170:171], 0, v[172:173]
	global_load_lds_dwordx4 v[170:171], off
	s_add_u32 s30, s100, s89
	s_add_u32 m0, s30, 0x3400
	v_lshl_add_u64 v[148:149], v[148:149], 0, s[68:69]
	global_load_lds_dwordx4 v[148:149], off

.LBB0_2119:
	s_nop 10
	v_max_f32_e32 v203, v80, v81
	v_max3_f32 v203, v203, v82, v83
	v_max3_f32 v203, v203, v84, v85
	v_max3_f32 v203, v203, v86, v87
	v_max3_f32 v203, v203, v88, v89
	v_max3_f32 v203, v203, v90, v91
	v_max3_f32 v203, v203, v92, v93
	v_max3_f32 v203, v203, v94, v95
	v_mov_b32_e32 v204, v203
	s_nop 1
	v_permlane32_swap_b32_e32 v203, v204
	v_max_f32_e32 v204, v203, v204
	v_max_f32_e32 v203, v64, v65
	v_max3_f32 v203, v203, v66, v67
	v_max3_f32 v203, v203, v68, v69
	v_max3_f32 v203, v203, v70, v71
	v_max3_f32 v203, v203, v72, v73
	v_max3_f32 v203, v203, v74, v75
	v_max3_f32 v203, v203, v76, v77
	v_max3_f32 v203, v203, v78, v79
	v_mov_b32_e32 v205, v203
	s_nop 1
	v_permlane32_swap_b32_e32 v203, v205
	v_max_f32_e32 v203, v203, v205
	v_max_f32_e32 v205, v204, v203
	v_cmp_lt_f32_e32 vcc, s82, v205
	v_min_f32_e32 v205, v204, v203
	v_cmp_gt_f32_e64 s[34:35], s83, v205
	s_and_b64 s[30:31], s[64:65], s[34:35]
	s_or_b64 s[30:31], vcc, s[30:31]
	s_and_b64 vcc, exec, s[30:31]
	s_cbranch_vccz .LBB0_2121
	v_max_f32_e32 v205, v204, v204
	v_max_f32_e32 v205, 0, v205
	v_cndmask_b32_e64 v204, v205, v204, s[64:65]
	v_exp_f32_e64 v206, -v204
	v_add_f32_e32 v199, v199, v204
	v_pk_add_f32 v[80:81], v[80:81], v[204:205] op_sel_hi:[1,0] neg_lo:[0,1] neg_hi:[0,1]
	v_pk_add_f32 v[82:83], v[82:83], v[204:205] op_sel_hi:[1,0] neg_lo:[0,1] neg_hi:[0,1]
	v_pk_add_f32 v[84:85], v[84:85], v[204:205] op_sel_hi:[1,0] neg_lo:[0,1] neg_hi:[0,1]
	v_pk_add_f32 v[86:87], v[86:87], v[204:205] op_sel_hi:[1,0] neg_lo:[0,1] neg_hi:[0,1]
	v_pk_add_f32 v[88:89], v[88:89], v[204:205] op_sel_hi:[1,0] neg_lo:[0,1] neg_hi:[0,1]
	v_pk_add_f32 v[90:91], v[90:91], v[204:205] op_sel_hi:[1,0] neg_lo:[0,1] neg_hi:[0,1]
	v_pk_add_f32 v[92:93], v[92:93], v[204:205] op_sel_hi:[1,0] neg_lo:[0,1] neg_hi:[0,1]
	v_pk_add_f32 v[94:95], v[94:95], v[204:205] op_sel_hi:[1,0] neg_lo:[0,1] neg_hi:[0,1]
	v_max_f32_e32 v204, v203, v203
	v_max_f32_e32 v204, 0, v204
	v_cndmask_b32_e64 v204, v204, v203, s[64:65]
	v_exp_f32_e64 v208, -v204
	v_mov_b32_e32 v209, v206
	v_pk_mul_f32 v[62:63], v[62:63], v[206:207] op_sel_hi:[1,0]
	v_pk_mul_f32 v[60:61], v[60:61], v[206:207] op_sel_hi:[1,0]
	v_pk_mul_f32 v[58:59], v[58:59], v[206:207] op_sel_hi:[1,0]
	v_pk_mul_f32 v[56:57], v[56:57], v[206:207] op_sel_hi:[1,0]
	v_pk_mul_f32 v[54:55], v[54:55], v[206:207] op_sel_hi:[1,0]
	v_pk_mul_f32 v[52:53], v[52:53], v[206:207] op_sel_hi:[1,0]
	v_pk_mul_f32 v[50:51], v[50:51], v[206:207] op_sel_hi:[1,0]
	v_pk_mul_f32 v[48:49], v[48:49], v[206:207] op_sel_hi:[1,0]
	v_pk_mul_f32 v[46:47], v[46:47], v[206:207] op_sel_hi:[1,0]
	v_pk_mul_f32 v[44:45], v[44:45], v[206:207] op_sel_hi:[1,0]
	v_pk_mul_f32 v[42:43], v[42:43], v[206:207] op_sel_hi:[1,0]
	v_pk_mul_f32 v[40:41], v[40:41], v[206:207] op_sel_hi:[1,0]
	v_pk_mul_f32 v[38:39], v[38:39], v[206:207] op_sel_hi:[1,0]
	v_pk_mul_f32 v[36:37], v[36:37], v[206:207] op_sel_hi:[1,0]
	v_pk_mul_f32 v[34:35], v[34:35], v[206:207] op_sel_hi:[1,0]
	v_pk_mul_f32 v[32:33], v[32:33], v[206:207] op_sel_hi:[1,0]
	v_add_f32_e32 v200, v200, v204
	v_pk_mul_f32 v[150:151], v[150:151], v[208:209]
	v_pk_add_f32 v[64:65], v[64:65], v[204:205] op_sel_hi:[1,0] neg_lo:[0,1] neg_hi:[0,1]
	v_pk_add_f32 v[66:67], v[66:67], v[204:205] op_sel_hi:[1,0] neg_lo:[0,1] neg_hi:[0,1]
	v_pk_add_f32 v[68:69], v[68:69], v[204:205] op_sel_hi:[1,0] neg_lo:[0,1] neg_hi:[0,1]
	v_pk_add_f32 v[70:71], v[70:71], v[204:205] op_sel_hi:[1,0] neg_lo:[0,1] neg_hi:[0,1]
	v_pk_add_f32 v[72:73], v[72:73], v[204:205] op_sel_hi:[1,0] neg_lo:[0,1] neg_hi:[0,1]
	v_pk_add_f32 v[74:75], v[74:75], v[204:205] op_sel_hi:[1,0] neg_lo:[0,1] neg_hi:[0,1]
	v_pk_add_f32 v[76:77], v[76:77], v[204:205] op_sel_hi:[1,0] neg_lo:[0,1] neg_hi:[0,1]
	v_pk_add_f32 v[78:79], v[78:79], v[204:205] op_sel_hi:[1,0] neg_lo:[0,1] neg_hi:[0,1]
	v_pk_mul_f32 v[30:31], v[30:31], v[208:209] op_sel_hi:[1,0]
	v_pk_mul_f32 v[28:29], v[28:29], v[208:209] op_sel_hi:[1,0]
	v_pk_mul_f32 v[26:27], v[26:27], v[208:209] op_sel_hi:[1,0]
	v_pk_mul_f32 v[24:25], v[24:25], v[208:209] op_sel_hi:[1,0]
	v_pk_mul_f32 v[22:23], v[22:23], v[208:209] op_sel_hi:[1,0]
	v_pk_mul_f32 v[20:21], v[20:21], v[208:209] op_sel_hi:[1,0]
	v_pk_mul_f32 v[18:19], v[18:19], v[208:209] op_sel_hi:[1,0]
	v_pk_mul_f32 v[16:17], v[16:17], v[208:209] op_sel_hi:[1,0]
	v_pk_mul_f32 v[14:15], v[14:15], v[208:209] op_sel_hi:[1,0]
	v_pk_mul_f32 v[12:13], v[12:13], v[208:209] op_sel_hi:[1,0]
	v_pk_mul_f32 v[10:11], v[10:11], v[208:209] op_sel_hi:[1,0]
	v_pk_mul_f32 v[8:9], v[8:9], v[208:209] op_sel_hi:[1,0]
	v_pk_mul_f32 v[6:7], v[6:7], v[208:209] op_sel_hi:[1,0]
	v_pk_mul_f32 v[4:5], v[4:5], v[208:209] op_sel_hi:[1,0]
	v_pk_mul_f32 v[2:3], v[2:3], v[208:209] op_sel_hi:[1,0]
	v_pk_mul_f32 v[0:1], v[0:1], v[208:209] op_sel_hi:[1,0]
	s_mov_b64 s[62:63], -1
.LBB0_2121:
	v_lshl_add_u32 v203, s68, 6, v202
	v_exp_f32_e32 v209, v80
	v_exp_f32_e32 v211, v81
	v_exp_f32_e32 v213, v82
	v_exp_f32_e32 v215, v83
	ds_read_b128 v[80:83], v203 offset:13312
	ds_read_b128 v[204:207], v203 offset:17920
	v_exp_f32_e32 v217, v84
	v_exp_f32_e32 v219, v85
	v_exp_f32_e32 v221, v86
	v_exp_f32_e32 v223, v87
	v_exp_f32_e32 v208, v64
	v_exp_f32_e32 v210, v65
	v_exp_f32_e32 v212, v66
	v_exp_f32_e32 v214, v67
	v_exp_f32_e32 v216, v68
	v_exp_f32_e32 v218, v69
	v_exp_f32_e32 v220, v70
	v_exp_f32_e32 v222, v71
	v_cvt_pk_bf16_f32 v64, v209, v211
	v_cvt_pk_bf16_f32 v65, v213, v215
	v_cvt_pk_bf16_f32 v66, v217, v219
	v_cvt_pk_bf16_f32 v67, v221, v223
	v_cvt_pk_bf16_f32 v68, v208, v210
	v_cvt_pk_bf16_f32 v69, v212, v214
	v_cvt_pk_bf16_f32 v70, v216, v218
	v_cvt_pk_bf16_f32 v71, v220, v222
	ds_read_b128 v[84:87], v203 offset:13344
	s_waitcnt lgkmcnt(0)
	v_mfma_f32_32x32x16_bf16 v[48:63], v[80:83], v[64:67], v[48:63]
	v_exp_f32_e32 v225, v88
	v_exp_f32_e32 v224, v72
	v_exp_f32_e32 v88, v73
	v_exp_f32_e32 v89, v89
	v_exp_f32_e32 v227, v90
	v_exp_f32_e32 v91, v91
	v_exp_f32_e32 v229, v92
	v_mfma_f32_32x32x16_bf16 v[16:31], v[80:83], v[68:71], v[16:31]
	ds_read_b128 v[80:83], v203 offset:17952
	v_exp_f32_e32 v93, v93
	v_exp_f32_e32 v231, v94
	v_exp_f32_e32 v95, v95
	v_exp_f32_e32 v226, v74
	v_exp_f32_e32 v90, v75
	v_exp_f32_e32 v228, v76
	v_mfma_f32_32x32x16_bf16 v[32:47], v[204:207], v[64:67], v[32:47]
	v_exp_f32_e32 v92, v77
	v_pk_add_f32 v[64:65], v[210:211], v[208:209]
	v_exp_f32_e32 v230, v78
	v_pk_add_f32 v[208:209], v[212:213], v[64:65]
	v_exp_f32_e32 v94, v79
	v_pk_add_f32 v[72:73], v[214:215], v[208:209]
	v_mfma_f32_32x32x16_bf16 v[0:15], v[204:207], v[68:71], v[0:15]
	v_add_f32_e64 v72, v216, v72
	v_add_f32_e64 v73, v217, v73
	v_cvt_pk_bf16_f32 v64, v225, v89
	v_add_f32_e64 v72, v218, v72
	v_add_f32_e64 v73, v219, v73
	v_cvt_pk_bf16_f32 v65, v227, v91
	v_pk_add_f32 v[72:73], v[220:221], v[72:73]
	v_cvt_pk_bf16_f32 v66, v229, v93
	v_pk_add_f32 v[72:73], v[222:223], v[72:73]
	v_cvt_pk_bf16_f32 v67, v231, v95
	v_cvt_pk_bf16_f32 v68, v224, v88
	v_cvt_pk_bf16_f32 v69, v226, v90
	v_cvt_pk_bf16_f32 v70, v228, v92
	v_cvt_pk_bf16_f32 v71, v230, v94
	v_pk_add_f32 v[72:73], v[224:225], v[72:73]
	v_mfma_f32_32x32x16_bf16 v[48:63], v[84:87], v[64:67], v[48:63]
	v_add_f32_e64 v72, v88, v72
	v_add_f32_e64 v73, v89, v73
	s_xor_b64 s[34:35], s[66:67], -1
	s_mov_b32 s68, 1
	s_mov_b64 s[66:67], 0
	s_and_b64 vcc, exec, s[34:35]
	v_mfma_f32_32x32x16_bf16 v[16:31], v[84:87], v[68:71], v[16:31]
	s_waitcnt lgkmcnt(0)
	v_mfma_f32_32x32x16_bf16 v[32:47], v[80:83], v[64:67], v[32:47]
	v_add_f32_e64 v64, v226, v72
	v_add_f32_e64 v65, v227, v73
	v_add_f32_e64 v64, v90, v64
	v_add_f32_e64 v65, v91, v65
	v_add_f32_e64 v64, v228, v64
	v_add_f32_e64 v65, v229, v65
	v_pk_add_f32 v[64:65], v[92:93], v[64:65]
	v_mfma_f32_32x32x16_bf16 v[0:15], v[80:83], v[68:71], v[0:15]
	v_add_f32_e64 v64, v230, v64
	v_add_f32_e64 v65, v231, v65
	v_add_f32_e64 v64, v94, v64
	v_add_f32_e64 v65, v95, v65
	v_add_f32_e64 v150, v150, v64
	v_add_f32_e64 v151, v151, v65
	s_cbranch_vccnz .LBB0_2123
	s_mov_b64 s[64:65], 0
	s_and_b64 vcc, exec, s[62:63]
	v_lshl_or_b32 v203, s68, 5, v190
	s_mov_b64 s[34:35], -1
	s_cbranch_vccz .LBB0_2116
	s_branch .LBB0_2117
